# attention finalize: lambda dot products one element per lane (1 round trip) + 6-hop bpermute butterfly instead of 8 serialized rounds of uniform loads
# speedup vs baseline: 1.0028x; 1.0028x over previous
; DI void attn_item(const Params& p, int l, int item, char* lds) {
;     ...
;   if (m == 0) {
;     float d1 = 0.f, d2 = 0.f;
;     for (int i = 0; i < 64; ++i) { d1 += p.lq1[l * 64 + i] * p.lk1[l * 64 + i]; d2 += p.lq2[l * 64 + i] * p.lk2[l * 64 + i]; }
;     const float lam_init = 0.8f - 0.6f * __expf(-0.3f * (float)l);
;     const float lam = __expf(d1) - __expf(d2) + lam_init;
;     float ss = 0.f;
; #pragma unroll
;     for (int vt = 0; vt < 4; ++vt)
; #pragma unroll
;       for (int e = 0; e < 16; ++e) {
;         const int vd = vt * 32 + (e & 3) + 8 * (e >> 2) + 4 * hh;
;         const float o2 = xb[(qh * 128 + vd) * 32 + q];
;         const float o = O[vt][e] - lam * o2; O[vt][e] = o; ss += o * o;
;       }
.LBB0_609:
	s_andn2_b64 vcc, exec, s[0:1]
	s_waitcnt lgkmcnt(0)
	s_barrier
	s_cbranch_vccnz .LBB0_571
	v_readlane_b32 s68, v251, 33
	v_readlane_b32 s72, v251, 37
	v_readlane_b32 s73, v251, 38
	v_readlane_b32 s74, v251, 39
	v_readlane_b32 s75, v251, 40
	v_readlane_b32 s76, v251, 41
	v_readlane_b32 s77, v251, 42
	v_readlane_b32 s78, v251, 43
	v_readlane_b32 s79, v251, 44
	v_readlane_b32 s80, v251, 45
	v_readlane_b32 s81, v251, 46
	v_readlane_b32 s82, v251, 47
	v_readlane_b32 s83, v251, 48
	s_mov_b32 s30, s87
	s_mov_b32 s27, s86
	s_mov_b32 s26, s85
	s_mov_b32 s21, s84
	v_readlane_b32 s72, v252, 3
	s_mov_b64 s[0:1], 0
	v_mov_b32_e32 v21, 0
	v_mov_b32_e32 v20, 0
	v_readlane_b32 s69, v251, 34
	v_readlane_b32 s70, v251, 35
	v_readlane_b32 s71, v251, 36
	v_readlane_b32 s84, v252, 15
	v_readlane_b32 s85, v252, 16
	v_readlane_b32 s86, v252, 17
	v_readlane_b32 s87, v252, 18
	v_readlane_b32 s73, v252, 4
	v_readlane_b32 s74, v252, 5
	v_readlane_b32 s75, v252, 6
	v_readlane_b32 s76, v252, 7
	v_readlane_b32 s77, v252, 8
	v_readlane_b32 s78, v252, 9
	v_readlane_b32 s79, v252, 10
	v_readlane_b32 s80, v252, 11
	v_readlane_b32 s81, v252, 12
	v_readlane_b32 s82, v252, 13
	v_readlane_b32 s83, v252, 14
	v_lshlrev_b32_e32 v24, 2, v163
	v_lshl_or_b32 v24, v169, 7, v24
	global_load_dword v25, v24, s[84:85]
	global_load_dword v26, v24, s[86:87]
	global_load_dword v27, v24, s[68:69]
	global_load_dword v28, v24, s[70:71]
	s_waitcnt vmcnt(0)
	v_mul_f32_e32 v21, v25, v26
	v_mul_f32_e32 v20, v27, v28
	v_xor_b32_e32 v25, 4, v24
	ds_bpermute_b32 v26, v25, v20
	ds_bpermute_b32 v27, v25, v21
	s_waitcnt lgkmcnt(0)
	v_add_f32_e32 v20, v20, v26
	v_add_f32_e32 v21, v21, v27
	v_xor_b32_e32 v25, 8, v24
	ds_bpermute_b32 v26, v25, v20
	ds_bpermute_b32 v27, v25, v21
	s_waitcnt lgkmcnt(0)
	v_add_f32_e32 v20, v20, v26
	v_add_f32_e32 v21, v21, v27
	v_xor_b32_e32 v25, 16, v24
	ds_bpermute_b32 v26, v25, v20
	ds_bpermute_b32 v27, v25, v21
	s_waitcnt lgkmcnt(0)
	v_add_f32_e32 v20, v20, v26
	v_add_f32_e32 v21, v21, v27
	v_xor_b32_e32 v25, 32, v24
	ds_bpermute_b32 v26, v25, v20
	ds_bpermute_b32 v27, v25, v21
	s_waitcnt lgkmcnt(0)
	v_add_f32_e32 v20, v20, v26
	v_add_f32_e32 v21, v21, v27
	v_xor_b32_e32 v25, 64, v24
	ds_bpermute_b32 v26, v25, v20
	ds_bpermute_b32 v27, v25, v21
	s_waitcnt lgkmcnt(0)
	v_add_f32_e32 v20, v20, v26
	v_add_f32_e32 v21, v21, v27
	v_xor_b32_e32 v25, 128, v24
	ds_bpermute_b32 v26, v25, v20
	ds_bpermute_b32 v27, v25, v21
	s_waitcnt lgkmcnt(0)
	v_add_f32_e32 v20, v20, v26
	v_add_f32_e32 v21, v21, v27
	v_mul_f32_e32 v0, 0x3fb8aa3b, v21
	v_mul_f32_e32 v20, 0x3fb8aa3b, v20
	v_exp_f32_e32 v0, v0
	v_exp_f32_e32 v20, v20
	s_and_b32 s0, s20, 0x1ffff80
	s_lshl_b32 s0, s0, 7
	s_mov_b32 s25, s97
	v_sub_f32_e32 v0, v0, v20
	v_lshl_or_b32 v20, v169, 9, s0
	v_lshl_or_b32 v91, v163, 2, v20
	v_add_u32_e32 v20, 0x400, v91
	ds_read2_b32 v[24:25], v91 offset1:32
	ds_read2_b32 v[26:27], v91 offset0:64 offset1:96
	ds_read2_b32 v[28:29], v20 offset1:32
	ds_read2_b32 v[30:31], v20 offset0:64 offset1:96
	v_add_u32_e32 v20, 0x800, v91
	ds_read2_b32 v[40:41], v20 offset1:32
	ds_read2_b32 v[42:43], v20 offset0:64 offset1:96
	v_add_u32_e32 v20, 0xc00, v91
	ds_read2_b32 v[44:45], v20 offset1:32
	ds_read2_b32 v[46:47], v20 offset0:64 offset1:96
	v_add_u32_e32 v20, 0x1000, v91
	ds_read2_b32 v[60:61], v20 offset1:32
	ds_read2_b32 v[62:63], v20 offset0:64 offset1:96
	v_add_u32_e32 v20, 0x1400, v91
	ds_read2_b32 v[78:79], v20 offset1:32
	ds_read2_b32 v[96:97], v20 offset0:64 offset1:96
	v_add_u32_e32 v20, 0x1800, v91
	ds_read2_b32 v[98:99], v20 offset1:32
	ds_read2_b32 v[100:101], v20 offset0:64 offset1:96
	v_add_u32_e32 v20, 0x1c00, v91
	ds_read2_b32 v[102:103], v20 offset1:32
	ds_read2_b32 v[104:105], v20 offset0:64 offset1:96
	v_add_u32_e32 v20, 0x2000, v91
	ds_read2_b32 v[106:107], v20 offset1:32
	ds_read2_b32 v[108:109], v20 offset0:64 offset1:96
	v_add_u32_e32 v20, 0x2400, v91
	ds_read2_b32 v[110:111], v20 offset1:32
	ds_read2_b32 v[112:113], v20 offset0:64 offset1:96
	v_add_u32_e32 v20, 0x2800, v91
	ds_read2_b32 v[114:115], v20 offset1:32
	ds_read2_b32 v[116:117], v20 offset0:64 offset1:96
	v_add_u32_e32 v20, 0x2c00, v91
	ds_read2_b32 v[118:119], v20 offset1:32
	ds_read2_b32 v[120:121], v20 offset0:64 offset1:96
	v_add_u32_e32 v20, 0x3000, v91
	ds_read2_b32 v[122:123], v20 offset1:32
	ds_read2_b32 v[124:125], v20 offset0:64 offset1:96
	v_add_u32_e32 v20, 0x3400, v91
	v_add_u32_e32 v92, 0x3c00, v91
	ds_read2_b32 v[126:127], v20 offset1:32
	ds_read2_b32 v[128:129], v20 offset0:64 offset1:96
	ds_read2_b32 v[20:21], v92 offset1:32
	v_add_u32_e32 v91, 0x3800, v91
	ds_read2_b32 v[92:93], v92 offset0:64 offset1:96
	ds_read2_b32 v[130:131], v91 offset1:32
	ds_read2_b32 v[132:133], v91 offset0:64 offset1:96
	v_add_f32_e32 v0, v190, v0
	v_mov_b32_e32 v169, v1
	s_waitcnt lgkmcnt(3)
	v_pk_fma_f32 v[20:21], v[0:1], v[20:21], v[18:19] op_sel_hi:[0,1,1] neg_lo:[1,0,0] neg_hi:[1,0,0]
	s_waitcnt lgkmcnt(2)
; DI void attn_item(const Params& p, int l, int item, char* lds) {
;     ...
;     float ss = 0.f;
; #pragma unroll
;     for (int vt = 0; vt < 4; ++vt)
; #pragma unroll
;       for (int e = 0; e < 16; ++e) {
;         const int vd = vt * 32 + (e & 3) + 8 * (e >> 2) + 4 * hh;
;         const float o2 = xb[(qh * 128 + vd) * 32 + q];
;         const float o = O[vt][e] - lam * o2; O[vt][e] = o; ss += o * o;
;       }
;     ss += __shfl_xor(ss, 32);
	v_pk_fma_f32 v[18:19], v[0:1], v[92:93], v[22:23] op_sel_hi:[0,1,1] neg_lo:[1,0,0] neg_hi:[1,0,0]
	v_lshl_add_u64 v[22:23], v[164:165], 0, s[24:25]
	v_lshl_add_u64 v[92:93], v[22:23], 0, v[168:169]
	s_mov_b64 s[0:1], 0x1d00
	v_lshl_add_u64 v[22:23], v[92:93], 0, s[0:1]
	s_movk_i32 s0, 0x1000
	v_add_co_u32_e32 v92, vcc, s0, v92
	v_pk_fma_f32 v[86:87], v[0:1], v[24:25], v[86:87] op_sel_hi:[0,1,1] neg_lo:[1,0,0] neg_hi:[1,0,0]
	s_nop 0
	v_addc_co_u32_e32 v93, vcc, 0, v93, vcc
	v_pk_fma_f32 v[88:89], v[0:1], v[26:27], v[88:89] op_sel_hi:[0,1,1] neg_lo:[1,0,0] neg_hi:[1,0,0]
	v_pk_mul_f32 v[144:145], v[86:87], v[86:87]
	global_load_dwordx2 v[140:141], v[92:93], off offset:3328
	s_nop 0
	global_load_dwordx4 v[92:95], v162, s[22:23]
	v_pk_mul_f32 v[142:143], v[88:89], v[88:89]
	v_pk_fma_f32 v[84:85], v[0:1], v[30:31], v[84:85] op_sel_hi:[0,1,1] neg_lo:[1,0,0] neg_hi:[1,0,0]
	v_pk_fma_f32 v[80:81], v[0:1], v[28:29], v[80:81] op_sel_hi:[0,1,1] neg_lo:[1,0,0] neg_hi:[1,0,0]
	v_pk_fma_f32 v[82:83], v[0:1], v[42:43], v[82:83] op_sel_hi:[0,1,1] neg_lo:[1,0,0] neg_hi:[1,0,0]
	v_pk_fma_f32 v[70:71], v[0:1], v[40:41], v[70:71] op_sel_hi:[0,1,1] neg_lo:[1,0,0] neg_hi:[1,0,0]
	v_pk_fma_f32 v[76:77], v[0:1], v[46:47], v[76:77] op_sel_hi:[0,1,1] neg_lo:[1,0,0] neg_hi:[1,0,0]
	v_pk_fma_f32 v[156:157], v[0:1], v[44:45], v[68:69] op_sel_hi:[0,1,1] neg_lo:[1,0,0] neg_hi:[1,0,0]
	v_pk_fma_f32 v[68:69], v[0:1], v[62:63], v[74:75] op_sel_hi:[0,1,1] neg_lo:[1,0,0] neg_hi:[1,0,0]
	v_pk_fma_f32 v[66:67], v[0:1], v[60:61], v[66:67] op_sel_hi:[0,1,1] neg_lo:[1,0,0] neg_hi:[1,0,0]
	v_pk_fma_f32 v[60:61], v[0:1], v[96:97], v[72:73] op_sel_hi:[0,1,1] neg_lo:[1,0,0] neg_hi:[1,0,0]
	v_pk_fma_f32 v[62:63], v[0:1], v[78:79], v[64:65] op_sel_hi:[0,1,1] neg_lo:[1,0,0] neg_hi:[1,0,0]
	v_pk_fma_f32 v[58:59], v[0:1], v[100:101], v[58:59] op_sel_hi:[0,1,1] neg_lo:[1,0,0] neg_hi:[1,0,0]
	v_pk_fma_f32 v[52:53], v[0:1], v[98:99], v[52:53] op_sel_hi:[0,1,1] neg_lo:[1,0,0] neg_hi:[1,0,0]
	v_pk_fma_f32 v[44:45], v[0:1], v[104:105], v[56:57] op_sel_hi:[0,1,1] neg_lo:[1,0,0] neg_hi:[1,0,0]
	v_pk_fma_f32 v[46:47], v[0:1], v[102:103], v[50:51] op_sel_hi:[0,1,1] neg_lo:[1,0,0] neg_hi:[1,0,0]
	v_pk_fma_f32 v[40:41], v[0:1], v[108:109], v[54:55] op_sel_hi:[0,1,1] neg_lo:[1,0,0] neg_hi:[1,0,0]
	v_pk_fma_f32 v[42:43], v[0:1], v[106:107], v[48:49] op_sel_hi:[0,1,1] neg_lo:[1,0,0] neg_hi:[1,0,0]
	v_pk_fma_f32 v[38:39], v[0:1], v[112:113], v[38:39] op_sel_hi:[0,1,1] neg_lo:[1,0,0] neg_hi:[1,0,0]
	v_pk_fma_f32 v[32:33], v[0:1], v[110:111], v[32:33] op_sel_hi:[0,1,1] neg_lo:[1,0,0] neg_hi:[1,0,0]
	v_pk_fma_f32 v[28:29], v[0:1], v[116:117], v[36:37] op_sel_hi:[0,1,1] neg_lo:[1,0,0] neg_hi:[1,0,0]
	v_pk_fma_f32 v[30:31], v[0:1], v[114:115], v[12:13] op_sel_hi:[0,1,1] neg_lo:[1,0,0] neg_hi:[1,0,0]
	v_pk_fma_f32 v[24:25], v[0:1], v[120:121], v[34:35] op_sel_hi:[0,1,1] neg_lo:[1,0,0] neg_hi:[1,0,0]
	v_pk_fma_f32 v[26:27], v[0:1], v[118:119], v[8:9] op_sel_hi:[0,1,1] neg_lo:[1,0,0] neg_hi:[1,0,0]
	v_pk_fma_f32 v[12:13], v[0:1], v[124:125], v[16:17] op_sel_hi:[0,1,1] neg_lo:[1,0,0] neg_hi:[1,0,0]
	v_pk_fma_f32 v[16:17], v[0:1], v[122:123], v[6:7] op_sel_hi:[0,1,1] neg_lo:[1,0,0] neg_hi:[1,0,0]
	v_pk_fma_f32 v[6:7], v[0:1], v[128:129], v[14:15] op_sel_hi:[0,1,1] neg_lo:[1,0,0] neg_hi:[1,0,0]
	v_pk_fma_f32 v[8:9], v[0:1], v[126:127], v[4:5] op_sel_hi:[0,1,1] neg_lo:[1,0,0] neg_hi:[1,0,0]
	s_waitcnt lgkmcnt(0)
	v_pk_fma_f32 v[4:5], v[0:1], v[132:133], v[10:11] op_sel_hi:[0,1,1] neg_lo:[1,0,0] neg_hi:[1,0,0]
	v_pk_fma_f32 v[2:3], v[0:1], v[130:131], v[2:3] op_sel_hi:[0,1,1] neg_lo:[1,0,0] neg_hi:[1,0,0]
	v_add_f32_e32 v0, v144, v145
	v_add_f32_e32 v0, v0, v142
	v_pk_mul_f32 v[148:149], v[80:81], v[80:81]
	v_add_f32_e32 v0, v0, v143
	v_add_f32_e32 v0, v0, v148
	v_pk_mul_f32 v[146:147], v[84:85], v[84:85]
	v_add_f32_e32 v0, v0, v149
	v_add_f32_e32 v0, v0, v146
	v_pk_mul_f32 v[152:153], v[70:71], v[70:71]
	v_add_f32_e32 v0, v0, v147
	v_add_f32_e32 v0, v0, v152
	v_pk_mul_f32 v[150:151], v[82:83], v[82:83]
	v_add_f32_e32 v0, v0, v153
	v_add_f32_e32 v0, v0, v150
	v_pk_mul_f32 v[158:159], v[156:157], v[156:157]
	v_add_f32_e32 v0, v0, v151
	v_add_f32_e32 v0, v0, v158
	v_pk_mul_f32 v[154:155], v[76:77], v[76:77]
	v_add_f32_e32 v0, v0, v159
	v_add_f32_e32 v0, v0, v154
	v_pk_mul_f32 v[164:165], v[66:67], v[66:67]
	v_add_f32_e32 v0, v0, v155
	v_add_f32_e32 v0, v0, v164
	v_pk_mul_f32 v[74:75], v[68:69], v[68:69]
	v_add_f32_e32 v0, v0, v165
	v_add_f32_e32 v0, v0, v74
	v_pk_mul_f32 v[64:65], v[62:63], v[62:63]
	v_add_f32_e32 v0, v0, v75
	v_add_f32_e32 v0, v0, v64
	v_pk_mul_f32 v[72:73], v[60:61], v[60:61]
	v_add_f32_e32 v0, v0, v65
	v_add_f32_e32 v0, v0, v72
	v_pk_mul_f32 v[96:97], v[52:53], v[52:53]
	v_add_f32_e32 v0, v0, v73
	v_add_f32_e32 v0, v0, v96
	v_pk_mul_f32 v[78:79], v[58:59], v[58:59]
	v_add_f32_e32 v0, v0, v97
	v_add_f32_e32 v0, v0, v78
	v_pk_mul_f32 v[50:51], v[46:47], v[46:47]
	v_add_f32_e32 v0, v0, v79
	v_add_f32_e32 v0, v0, v50
	v_pk_mul_f32 v[56:57], v[44:45], v[44:45]
	v_add_f32_e32 v0, v0, v51
	v_add_f32_e32 v0, v0, v56
	v_pk_mul_f32 v[48:49], v[42:43], v[42:43]
	v_add_f32_e32 v0, v0, v57
	v_add_f32_e32 v0, v0, v48
	v_pk_mul_f32 v[54:55], v[40:41], v[40:41]
	v_add_f32_e32 v0, v0, v49
	v_add_f32_e32 v0, v0, v54
	v_pk_mul_f32 v[100:101], v[32:33], v[32:33]
	v_add_f32_e32 v0, v0, v55
	v_add_f32_e32 v0, v0, v100
	v_pk_mul_f32 v[98:99], v[38:39], v[38:39]
	v_add_f32_e32 v0, v0, v101
	v_add_f32_e32 v0, v0, v98
	v_pk_mul_f32 v[102:103], v[30:31], v[30:31]
	v_add_f32_e32 v0, v0, v99
	v_add_f32_e32 v0, v0, v102
	v_pk_mul_f32 v[36:37], v[28:29], v[28:29]
	v_add_f32_e32 v0, v0, v103
	v_add_f32_e32 v0, v0, v36
	v_pk_mul_f32 v[104:105], v[26:27], v[26:27]
	v_add_f32_e32 v0, v0, v37
	v_add_f32_e32 v0, v0, v104
	v_pk_mul_f32 v[34:35], v[24:25], v[24:25]
	v_add_f32_e32 v0, v0, v105
	v_add_f32_e32 v0, v0, v34
	v_pk_mul_f32 v[108:109], v[16:17], v[16:17]
	v_add_f32_e32 v0, v0, v35
	v_add_f32_e32 v0, v0, v108
	v_pk_mul_f32 v[106:107], v[12:13], v[12:13]
	v_add_f32_e32 v0, v0, v109
	v_add_f32_e32 v0, v0, v106
	v_pk_mul_f32 v[110:111], v[8:9], v[8:9]
	v_add_f32_e32 v0, v0, v107
	v_add_f32_e32 v0, v0, v110
	v_pk_mul_f32 v[14:15], v[6:7], v[6:7]
	v_add_f32_e32 v0, v0, v111
	v_add_f32_e32 v0, v0, v14
	v_pk_mul_f32 v[112:113], v[2:3], v[2:3]
	v_add_f32_e32 v0, v0, v15
	v_add_f32_e32 v0, v0, v112
	v_pk_mul_f32 v[10:11], v[4:5], v[4:5]
	v_add_f32_e32 v0, v0, v113
	v_add_f32_e32 v0, v0, v10
	v_pk_mul_f32 v[134:135], v[20:21], v[20:21]
	v_add_f32_e32 v0, v0, v11
	v_add_f32_e32 v0, v0, v134
	v_pk_mul_f32 v[136:137], v[18:19], v[18:19]
	v_add_f32_e32 v0, v0, v135
	v_add_f32_e32 v0, v0, v136
	v_add_f32_e32 v0, v0, v137
	ds_bpermute_b32 v10, v90, v0
	s_waitcnt vmcnt(1)
; DI unsigned pk2(float a, float b) { f32x2 v = {a, b}; bfv2 r = __builtin_convertvector(v, bfv2); return __builtin_bit_cast(unsigned, r); }
; DI float bf_lo(unsigned u) { return __uint_as_float(u << 16); }
; DI float bf_hi(unsigned u) { return __uint_as_float(u & 0xffff0000u); }
; DI void attn_item(const Params& p, int l, int item, char* lds) {
;     ...
;     ss += __shfl_xor(ss, 32);
;     const float rstd = rsqrtf(ss * (1.0f / 128.0f) + 1e-5f) * (1.0f - lam_init);
;     const size_t row = (size_t)(qrow0 + qh * 32 + q);
;     const float* sg = p.subln_g + l * 128;
; #pragma unroll
;     for (int vt = 0; vt < 4; ++vt)
; #pragma unroll
;       for (int e4 = 0; e4 < 4; ++e4) {
;         const int vd = vt * 32 + 8 * e4 + 4 * hh;
;         const u32x2 gu = *(const u32x2*)(p.z + row * NZ + C_GA + h * 128 + vd);
;         const f32x4 gv = *(const f32x4*)(sg + vd);
;         const float y0 = O[vt][4 * e4 + 0] * rstd * gv[0] * bf_lo(gu[0]);
;         const float y1 = O[vt][4 * e4 + 1] * rstd * gv[1] * bf_hi(gu[0]);
;         const float y2 = O[vt][4 * e4 + 2] * rstd * gv[2] * bf_lo(gu[1]);
;         const float y3 = O[vt][4 * e4 + 3] * rstd * gv[3] * bf_hi(gu[1]);
;         u32x2 ov; ov[0] = pk2(y0, y1); ov[1] = pk2(y2, y3);
;         *(u32x2*)(p.o_a + row * 512 + h * 128 + vd) = ov;
;       }
	v_lshlrev_b32_e32 v14, 16, v140
	v_and_b32_e32 v15, 0xffff0000, v140
	v_lshlrev_b64 v[138:139], 10, v[166:167]
	v_lshlrev_b32_e32 v34, 16, v141
	s_waitcnt lgkmcnt(0)
	v_add_f32_e32 v0, v0, v10
	v_mov_b32_e32 v10, 0x3727c5ac
	v_fmamk_f32 v0, v0, 0x3c000000, v10
	v_mul_f32_e32 v10, 0x4b800000, v0
	v_cmp_gt_f32_e32 vcc, s34, v0
	v_and_b32_e32 v35, 0xffff0000, v141
	s_mov_b32 s84, s21
	v_cndmask_b32_e32 v0, v0, v10, vcc
	v_rsq_f32_e32 v0, v0
	v_lshl_add_u64 v[10:11], s[54:55], 0, v[138:139]
	v_lshl_add_u64 v[10:11], v[10:11], 0, s[24:25]
	v_lshl_add_u64 v[10:11], v[10:11], 0, v[168:169]
	v_mul_f32_e32 v36, 0x45800000, v0
	v_cndmask_b32_e32 v0, v0, v36, vcc
	v_mul_f32_e32 v0, v191, v0
	v_pk_mul_f32 v[36:37], v[86:87], v[0:1] op_sel_hi:[1,0]
	v_pk_mul_f32 v[48:49], v[80:81], v[0:1] op_sel_hi:[1,0]
	s_waitcnt vmcnt(0)
	v_pk_mul_f32 v[36:37], v[92:93], v[36:37]
	v_pk_mul_f32 v[50:51], v[82:83], v[0:1] op_sel_hi:[1,0]
	v_pk_mul_f32 v[14:15], v[36:37], v[14:15]
	v_pk_mul_f32 v[36:37], v[88:89], v[0:1] op_sel_hi:[1,0]
	v_cvt_pk_bf16_f32 v14, v14, v15
	v_pk_mul_f32 v[36:37], v[94:95], v[36:37]
	v_pk_mul_f32 v[46:47], v[46:47], v[0:1] op_sel_hi:[1,0]
	v_pk_mul_f32 v[34:35], v[36:37], v[34:35]
	v_pk_mul_f32 v[44:45], v[44:45], v[0:1] op_sel_hi:[1,0]
	v_cvt_pk_bf16_f32 v15, v34, v35
	global_store_dwordx2 v[10:11], v[14:15], off
	global_load_dwordx4 v[34:37], v162, s[22:23] offset:32
	s_nop 0
	global_load_dwordx2 v[14:15], v[22:23], off offset:16
	v_pk_mul_f32 v[42:43], v[42:43], v[0:1] op_sel_hi:[1,0]
	v_pk_mul_f32 v[40:41], v[40:41], v[0:1] op_sel_hi:[1,0]
	v_pk_mul_f32 v[32:33], v[32:33], v[0:1] op_sel_hi:[1,0]
	v_pk_mul_f32 v[38:39], v[38:39], v[0:1] op_sel_hi:[1,0]
	v_pk_mul_f32 v[30:31], v[30:31], v[0:1] op_sel_hi:[1,0]
	v_pk_mul_f32 v[28:29], v[28:29], v[0:1] op_sel_hi:[1,0]
	v_pk_mul_f32 v[26:27], v[26:27], v[0:1] op_sel_hi:[1,0]
	v_pk_mul_f32 v[24:25], v[24:25], v[0:1] op_sel_hi:[1,0]
	v_pk_mul_f32 v[16:17], v[16:17], v[0:1] op_sel_hi:[1,0]
	v_pk_mul_f32 v[12:13], v[12:13], v[0:1] op_sel_hi:[1,0]
	v_pk_mul_f32 v[8:9], v[8:9], v[0:1] op_sel_hi:[1,0]
	v_pk_mul_f32 v[6:7], v[6:7], v[0:1] op_sel_hi:[1,0]
	v_pk_mul_f32 v[2:3], v[2:3], v[0:1] op_sel_hi:[1,0]
	v_pk_mul_f32 v[4:5], v[4:5], v[0:1] op_sel_hi:[1,0]
	s_mov_b32 s85, s26
	s_mov_b32 s86, s27
	s_mov_b32 s87, s30
	s_waitcnt vmcnt(1)
	v_pk_mul_f32 v[34:35], v[34:35], v[48:49]
	s_waitcnt vmcnt(0)
	v_lshlrev_b32_e32 v48, 16, v14
	v_and_b32_e32 v49, 0xffff0000, v14
	v_pk_mul_f32 v[34:35], v[34:35], v[48:49]
	v_pk_mul_f32 v[48:49], v[84:85], v[0:1] op_sel_hi:[1,0]
	v_lshlrev_b32_e32 v14, 16, v15
	v_pk_mul_f32 v[36:37], v[36:37], v[48:49]
	v_and_b32_e32 v15, 0xffff0000, v15
	v_pk_mul_f32 v[14:15], v[36:37], v[14:15]
	v_cvt_pk_bf16_f32 v34, v34, v35
	v_cvt_pk_bf16_f32 v35, v14, v15
	global_store_dwordx2 v[10:11], v[34:35], off offset:16
	global_load_dwordx4 v[34:37], v162, s[22:23] offset:64
	s_nop 0
	global_load_dwordx2 v[14:15], v[22:23], off offset:32
	v_pk_mul_f32 v[48:49], v[70:71], v[0:1] op_sel_hi:[1,0]
	s_waitcnt vmcnt(1)
	v_pk_mul_f32 v[36:37], v[36:37], v[50:51]
	v_pk_mul_f32 v[34:35], v[34:35], v[48:49]
	s_waitcnt vmcnt(0)
	v_lshlrev_b32_e32 v48, 16, v14
	v_and_b32_e32 v49, 0xffff0000, v14
	v_lshlrev_b32_e32 v14, 16, v15
	v_and_b32_e32 v15, 0xffff0000, v15
	v_pk_mul_f32 v[34:35], v[34:35], v[48:49]
	v_pk_mul_f32 v[14:15], v[36:37], v[14:15]
	v_cvt_pk_bf16_f32 v34, v34, v35
	v_cvt_pk_bf16_f32 v35, v14, v15
	global_store_dwordx2 v[10:11], v[34:35], off offset:32
	global_load_dwordx4 v[34:37], v162, s[22:23] offset:96
	s_nop 0
	global_load_dwordx2 v[14:15], v[22:23], off offset:48
	v_pk_mul_f32 v[48:49], v[156:157], v[0:1] op_sel_hi:[1,0]
	v_pk_mul_f32 v[50:51], v[76:77], v[0:1] op_sel_hi:[1,0]
	s_waitcnt vmcnt(1)
	v_pk_mul_f32 v[34:35], v[34:35], v[48:49]
	s_waitcnt vmcnt(0)
	v_lshlrev_b32_e32 v48, 16, v14
	v_and_b32_e32 v49, 0xffff0000, v14
	v_pk_mul_f32 v[36:37], v[36:37], v[50:51]
	v_lshlrev_b32_e32 v14, 16, v15
	v_and_b32_e32 v15, 0xffff0000, v15
	v_pk_mul_f32 v[34:35], v[34:35], v[48:49]
	v_pk_mul_f32 v[14:15], v[36:37], v[14:15]
	v_cvt_pk_bf16_f32 v34, v34, v35
	v_cvt_pk_bf16_f32 v35, v14, v15
	global_store_dwordx2 v[10:11], v[34:35], off offset:48
	global_load_dwordx4 v[34:37], v162, s[22:23] offset:128
	s_nop 0
	global_load_dwordx2 v[14:15], v[22:23], off offset:64
	v_pk_mul_f32 v[48:49], v[66:67], v[0:1] op_sel_hi:[1,0]
	v_pk_mul_f32 v[50:51], v[68:69], v[0:1] op_sel_hi:[1,0]
	s_waitcnt vmcnt(1)
	v_pk_mul_f32 v[34:35], v[48:49], v[34:35]
	s_waitcnt vmcnt(0)
	v_lshlrev_b32_e32 v48, 16, v14
	v_and_b32_e32 v49, 0xffff0000, v14
	v_pk_mul_f32 v[36:37], v[50:51], v[36:37]
	v_lshlrev_b32_e32 v14, 16, v15
	v_and_b32_e32 v15, 0xffff0000, v15
	v_pk_mul_f32 v[34:35], v[34:35], v[48:49]
	v_pk_mul_f32 v[14:15], v[36:37], v[14:15]
	v_cvt_pk_bf16_f32 v34, v34, v35
	v_cvt_pk_bf16_f32 v35, v14, v15
	global_store_dwordx2 v[10:11], v[34:35], off offset:64
	global_load_dwordx4 v[34:37], v162, s[22:23] offset:160
	s_nop 0
	global_load_dwordx2 v[14:15], v[22:23], off offset:80
	v_pk_mul_f32 v[48:49], v[62:63], v[0:1] op_sel_hi:[1,0]
	v_pk_mul_f32 v[50:51], v[60:61], v[0:1] op_sel_hi:[1,0]
	s_waitcnt vmcnt(1)
	v_pk_mul_f32 v[34:35], v[48:49], v[34:35]
	s_waitcnt vmcnt(0)
	v_lshlrev_b32_e32 v48, 16, v14
	v_and_b32_e32 v49, 0xffff0000, v14
	v_pk_mul_f32 v[36:37], v[50:51], v[36:37]
	v_lshlrev_b32_e32 v14, 16, v15
	v_and_b32_e32 v15, 0xffff0000, v15
	v_pk_mul_f32 v[34:35], v[34:35], v[48:49]
	v_pk_mul_f32 v[14:15], v[36:37], v[14:15]
	v_cvt_pk_bf16_f32 v34, v34, v35
	v_cvt_pk_bf16_f32 v35, v14, v15
	global_store_dwordx2 v[10:11], v[34:35], off offset:80
	global_load_dwordx4 v[34:37], v162, s[22:23] offset:192
	s_nop 0
	global_load_dwordx2 v[14:15], v[22:23], off offset:96
	v_pk_mul_f32 v[48:49], v[52:53], v[0:1] op_sel_hi:[1,0]
	v_pk_mul_f32 v[50:51], v[58:59], v[0:1] op_sel_hi:[1,0]
	s_waitcnt vmcnt(1)
; DI unsigned pk2(float a, float b) { f32x2 v = {a, b}; bfv2 r = __builtin_convertvector(v, bfv2); return __builtin_bit_cast(unsigned, r); }
; DI float bf_lo(unsigned u) { return __uint_as_float(u << 16); }
; DI float bf_hi(unsigned u) { return __uint_as_float(u & 0xffff0000u); }
; DI void attn_item(const Params& p, int l, int item, char* lds) {
;     ...
; #pragma unroll
;     for (int vt = 0; vt < 4; ++vt)
; #pragma unroll
;       for (int e4 = 0; e4 < 4; ++e4) {
;         const int vd = vt * 32 + 8 * e4 + 4 * hh;
;         const u32x2 gu = *(const u32x2*)(p.z + row * NZ + C_GA + h * 128 + vd);
;         const f32x4 gv = *(const f32x4*)(sg + vd);
;         const float y0 = O[vt][4 * e4 + 0] * rstd * gv[0] * bf_lo(gu[0]);
;         const float y1 = O[vt][4 * e4 + 1] * rstd * gv[1] * bf_hi(gu[0]);
;         const float y2 = O[vt][4 * e4 + 2] * rstd * gv[2] * bf_lo(gu[1]);
;         const float y3 = O[vt][4 * e4 + 3] * rstd * gv[3] * bf_hi(gu[1]);
;         u32x2 ov; ov[0] = pk2(y0, y1); ov[1] = pk2(y2, y3);
;         *(u32x2*)(p.o_a + row * 512 + h * 128 + vd) = ov;
;       }
	v_pk_mul_f32 v[34:35], v[48:49], v[34:35]
	s_waitcnt vmcnt(0)
	v_lshlrev_b32_e32 v48, 16, v14
	v_and_b32_e32 v49, 0xffff0000, v14
	v_pk_mul_f32 v[36:37], v[50:51], v[36:37]
	v_lshlrev_b32_e32 v14, 16, v15
	v_and_b32_e32 v15, 0xffff0000, v15
	v_pk_mul_f32 v[34:35], v[34:35], v[48:49]
	v_pk_mul_f32 v[14:15], v[36:37], v[14:15]
	v_cvt_pk_bf16_f32 v34, v34, v35
	v_cvt_pk_bf16_f32 v35, v14, v15
	global_store_dwordx2 v[10:11], v[34:35], off offset:96
	global_load_dwordx4 v[34:37], v162, s[22:23] offset:224
	s_nop 0
	global_load_dwordx2 v[14:15], v[22:23], off offset:112
	s_waitcnt vmcnt(1)
	v_pk_mul_f32 v[34:35], v[46:47], v[34:35]
	s_waitcnt vmcnt(0)
	v_lshlrev_b32_e32 v46, 16, v14
	v_and_b32_e32 v47, 0xffff0000, v14
	v_pk_mul_f32 v[36:37], v[44:45], v[36:37]
	v_lshlrev_b32_e32 v14, 16, v15
	v_and_b32_e32 v15, 0xffff0000, v15
	v_pk_mul_f32 v[34:35], v[34:35], v[46:47]
	v_pk_mul_f32 v[14:15], v[36:37], v[14:15]
	v_cvt_pk_bf16_f32 v34, v34, v35
	v_cvt_pk_bf16_f32 v35, v14, v15
	global_store_dwordx2 v[10:11], v[34:35], off offset:112
	global_load_dwordx4 v[34:37], v162, s[22:23] offset:256
	s_nop 0
	global_load_dwordx2 v[14:15], v[22:23], off offset:128
	s_waitcnt vmcnt(1)
	v_pk_mul_f32 v[34:35], v[42:43], v[34:35]
	s_waitcnt vmcnt(0)
	v_lshlrev_b32_e32 v42, 16, v14
	v_and_b32_e32 v43, 0xffff0000, v14
	v_pk_mul_f32 v[36:37], v[40:41], v[36:37]
	v_lshlrev_b32_e32 v14, 16, v15
	v_and_b32_e32 v15, 0xffff0000, v15
	v_pk_mul_f32 v[34:35], v[34:35], v[42:43]
	v_pk_mul_f32 v[14:15], v[36:37], v[14:15]
	v_cvt_pk_bf16_f32 v34, v34, v35
	v_cvt_pk_bf16_f32 v35, v14, v15
	global_store_dwordx2 v[10:11], v[34:35], off offset:128
	global_load_dwordx4 v[34:37], v162, s[22:23] offset:288
	s_nop 0
	global_load_dwordx2 v[14:15], v[22:23], off offset:144
	s_waitcnt vmcnt(1)
	v_pk_mul_f32 v[32:33], v[32:33], v[34:35]
	s_waitcnt vmcnt(0)
	v_lshlrev_b32_e32 v34, 16, v14
	v_and_b32_e32 v35, 0xffff0000, v14
	v_pk_mul_f32 v[36:37], v[38:39], v[36:37]
	v_lshlrev_b32_e32 v14, 16, v15
	v_and_b32_e32 v15, 0xffff0000, v15
	v_pk_mul_f32 v[32:33], v[32:33], v[34:35]
	v_pk_mul_f32 v[14:15], v[36:37], v[14:15]
	v_cvt_pk_bf16_f32 v32, v32, v33
	v_cvt_pk_bf16_f32 v33, v14, v15
	global_store_dwordx2 v[10:11], v[32:33], off offset:144
	global_load_dwordx4 v[32:35], v162, s[22:23] offset:320
	s_nop 0
	global_load_dwordx2 v[14:15], v[22:23], off offset:160
	s_waitcnt vmcnt(1)
	v_pk_mul_f32 v[30:31], v[30:31], v[32:33]
	s_waitcnt vmcnt(0)
	v_lshlrev_b32_e32 v32, 16, v14
	v_and_b32_e32 v33, 0xffff0000, v14
	v_pk_mul_f32 v[28:29], v[28:29], v[34:35]
	v_lshlrev_b32_e32 v14, 16, v15
	v_and_b32_e32 v15, 0xffff0000, v15
	v_pk_mul_f32 v[30:31], v[30:31], v[32:33]
	v_pk_mul_f32 v[14:15], v[28:29], v[14:15]
	v_cvt_pk_bf16_f32 v28, v30, v31
	v_cvt_pk_bf16_f32 v29, v14, v15
	global_store_dwordx2 v[10:11], v[28:29], off offset:160
	global_load_dwordx4 v[28:31], v162, s[22:23] offset:352
	s_nop 0
	global_load_dwordx2 v[14:15], v[22:23], off offset:176
	s_waitcnt vmcnt(1)
	v_pk_mul_f32 v[26:27], v[26:27], v[28:29]
	s_waitcnt vmcnt(0)
	v_lshlrev_b32_e32 v28, 16, v14
	v_and_b32_e32 v29, 0xffff0000, v14
	v_pk_mul_f32 v[24:25], v[24:25], v[30:31]
	v_lshlrev_b32_e32 v14, 16, v15
	v_and_b32_e32 v15, 0xffff0000, v15
	v_pk_mul_f32 v[26:27], v[26:27], v[28:29]
	v_pk_mul_f32 v[14:15], v[24:25], v[14:15]
	v_cvt_pk_bf16_f32 v24, v26, v27
	v_cvt_pk_bf16_f32 v25, v14, v15
	global_store_dwordx2 v[10:11], v[24:25], off offset:176
	global_load_dwordx4 v[24:27], v162, s[22:23] offset:384
	s_nop 0
	global_load_dwordx2 v[14:15], v[22:23], off offset:192
	s_waitcnt vmcnt(1)
	v_pk_mul_f32 v[16:17], v[16:17], v[24:25]
	s_waitcnt vmcnt(0)
	v_lshlrev_b32_e32 v24, 16, v14
	v_and_b32_e32 v25, 0xffff0000, v14
	v_pk_mul_f32 v[12:13], v[12:13], v[26:27]
	v_lshlrev_b32_e32 v14, 16, v15
	v_and_b32_e32 v15, 0xffff0000, v15
	v_pk_mul_f32 v[16:17], v[16:17], v[24:25]
	v_pk_mul_f32 v[12:13], v[12:13], v[14:15]
	v_cvt_pk_bf16_f32 v14, v16, v17
	v_cvt_pk_bf16_f32 v15, v12, v13
	global_store_dwordx2 v[10:11], v[14:15], off offset:192
	global_load_dwordx4 v[12:15], v162, s[22:23] offset:416
	s_nop 0
	global_load_dwordx2 v[16:17], v[22:23], off offset:208
	s_waitcnt vmcnt(1)
	v_pk_mul_f32 v[8:9], v[8:9], v[12:13]
	s_waitcnt vmcnt(0)
	v_lshlrev_b32_e32 v12, 16, v16
	v_and_b32_e32 v13, 0xffff0000, v16
	v_pk_mul_f32 v[6:7], v[6:7], v[14:15]
	v_lshlrev_b32_e32 v14, 16, v17
	v_and_b32_e32 v15, 0xffff0000, v17
	v_pk_mul_f32 v[8:9], v[8:9], v[12:13]
	v_pk_mul_f32 v[6:7], v[6:7], v[14:15]
	v_cvt_pk_bf16_f32 v8, v8, v9
	v_cvt_pk_bf16_f32 v9, v6, v7
	global_store_dwordx2 v[10:11], v[8:9], off offset:208
	global_load_dwordx4 v[6:9], v162, s[22:23] offset:448
	s_nop 0
	global_load_dwordx2 v[12:13], v[22:23], off offset:224
	s_waitcnt vmcnt(1)
	v_pk_mul_f32 v[2:3], v[2:3], v[6:7]
	s_waitcnt vmcnt(0)
	v_lshlrev_b32_e32 v6, 16, v12
	v_and_b32_e32 v7, 0xffff0000, v12
	v_pk_mul_f32 v[4:5], v[4:5], v[8:9]
	v_lshlrev_b32_e32 v8, 16, v13
	v_and_b32_e32 v9, 0xffff0000, v13
	v_pk_mul_f32 v[2:3], v[2:3], v[6:7]
	v_pk_mul_f32 v[4:5], v[4:5], v[8:9]
	v_cvt_pk_bf16_f32 v2, v2, v3
	v_cvt_pk_bf16_f32 v3, v4, v5
	global_store_dwordx2 v[10:11], v[2:3], off offset:224
	global_load_dwordx4 v[2:5], v162, s[22:23] offset:480
	s_nop 0
	global_load_dwordx2 v[6:7], v[22:23], off offset:240
	v_pk_mul_f32 v[8:9], v[20:21], v[0:1] op_sel_hi:[1,0]
	v_pk_mul_f32 v[12:13], v[18:19], v[0:1] op_sel_hi:[1,0]
	s_waitcnt vmcnt(1)
	v_pk_mul_f32 v[2:3], v[8:9], v[2:3]
	s_waitcnt vmcnt(0)
	v_lshlrev_b32_e32 v8, 16, v6
	v_and_b32_e32 v9, 0xffff0000, v6
	v_pk_mul_f32 v[4:5], v[12:13], v[4:5]
	v_lshlrev_b32_e32 v6, 16, v7
	v_and_b32_e32 v7, 0xffff0000, v7
	v_pk_mul_f32 v[2:3], v[2:3], v[8:9]
	v_pk_mul_f32 v[4:5], v[4:5], v[6:7]
	v_cvt_pk_bf16_f32 v2, v2, v3
	v_cvt_pk_bf16_f32 v3, v4, v5
	global_store_dwordx2 v[10:11], v[2:3], off offset:240
	s_branch .LBB0_571
